# P1+P7 int8 GEMM K-loops: LDS-DMA staging rebalanced to 4 per segment (A[b][0] pieces staged one phase later), SP2 waits vmcnt(6); on top of attention load hoist
# speedup vs baseline: 1.0112x; 1.0037x over previous
; #define PG8_STAGE(bufoff, gbase, voff) do { _Pragma("unroll") for (int _i = 0; _i < 2; ++_i) \
;         __builtin_amdgcn_global_load_lds((const unsigned*)((const char*)(gbase) + (voff)[_i]), (LAS unsigned*)(lds + (bufoff) + ldsw + _i * 8192), 16, 0, 0); } while (0)
; #define PG8_LDA(dst, b, h) do { _Pragma("unroll") for (int m = 0; m < 4; ++m) _Pragma("unroll") for (int k = 0; k < 2; ++k) dst[m][k] = *(const LAS bf16x8*)(lds + PG8_SA(b, h) + aoff + m * 2048 + k * 1024); } while (0)
; #define PG8_LDB(dst, b, h) do { _Pragma("unroll") for (int n = 0; n < 2; ++n) _Pragma("unroll") for (int k = 0; k < 2; ++k) dst[n][k] = *(const LAS bf16x8*)(lds + PG8_SB(b, h) + boff + n * 2048 + k * 1024); } while (0)
; #define PG8_WAIT_V(n) asm volatile("s_waitcnt vmcnt(" #n ")" ::: "memory")
; #define PG8_WAIT_L(n) asm volatile("s_waitcnt lgkmcnt(" #n ")" ::: "memory")
; #define PG8_BAR __builtin_amdgcn_s_barrier()
; #define PG8_SCHED __builtin_amdgcn_sched_barrier(0)
; template <class Epi, class Sched, bool I8 = false>
; __device__ __forceinline__ void gemm_phase(LAS unsigned char* lds, const Gemm g, const Sched& S, const Epi& E) {
;     ...
;         for (int t = 0; t < nt; t += 2) {
;             const bool last = (t == nt - 2);
;             const char* a1 = cA + (size_t)(t + 1) * kstep;
;             const char* a2 = last ? nA : cA + (size_t)(t + 2) * kstep; const char* b2 = last ? nB : cB + (size_t)(t + 2) * kstep;
;             const char* a3 = a2 + kstep; const char* b3 = b2 + kstep;
;             PG8_LDB(B0, 0, 0); PG8_LDB(B1, 0, 1); PG8_SCHED; PG8_LDA(At, 0, 0); PG8_STAGE(PG8_SA(1, 1), a1 + hstepA, voffA);
;             PG8_WAIT_V(8); PG8_WAIT_L(0); PG8_BAR; PG8_MMA(0, 0, At, B0); PG8_MMA(0, 1, At, B1); PG8_BAR; PG8_SCHED;
;             PG8_LDA(At, 0, 1); PG8_STAGE(PG8_SB(0, 0), b2, voffB); PG8_STAGE(PG8_SB(0, 1), b2 + hstepB, voffB); PG8_STAGE(PG8_SA(0, 0), a2, voffA);
;             PG8_WAIT_V(8); PG8_WAIT_L(0); PG8_BAR; PG8_MMA(1, 0, At, B0); PG8_MMA(1, 1, At, B1); PG8_BAR; PG8_SCHED;
.LBB0_1169:
	ds_read_b128 v[90:93], v169
	ds_read_b128 v[98:101], v169 offset:1024
	ds_read_b128 v[172:175], v169 offset:2048
	ds_read_b128 v[176:179], v169 offset:3072
	ds_read_b128 v[180:183], v170
	ds_read_b128 v[184:187], v170 offset:1024
	ds_read_b128 v[188:191], v170 offset:2048
	ds_read_b128 v[192:195], v170 offset:3072
	s_add_u32 s22, s20, 0x4000
	s_addc_u32 s23, s21, 0
	s_cmp_eq_u32 s53, 28
	s_cselect_b32 s26, s49, s22
	s_cselect_b32 s27, s13, s23
	s_cselect_b32 s24, s50, s51
	s_cselect_b32 s25, s11, s52
	s_add_u32 s22, s26, 0x8000
	s_addc_u32 s23, s27, 0
	s_sub_u32 s54, s20, 0x4000
	s_subb_u32 s55, s21, 0
	v_lshl_add_u64 v[158:159], s[54:55], 0, v[144:145]
	s_mov_b32 m0, s43
	s_nop 0
	global_load_lds_dwordx4 v[158:159], off
	v_lshl_add_u64 v[158:159], s[54:55], 0, v[140:141]
	s_mov_b32 m0, s44
	s_nop 0
	global_load_lds_dwordx4 v[158:159], off
	v_lshl_add_u64 v[158:159], s[20:21], 0, v[148:149]
	s_add_i32 m0, s36, 0xc000
	ds_read_b128 v[196:199], v171
	ds_read_b128 v[200:203], v171 offset:1024
	ds_read_b128 v[204:207], v171 offset:2048
	ds_read_b128 v[208:211], v171 offset:3072
	ds_read_b128 v[212:215], v171 offset:4096
	ds_read_b128 v[216:219], v171 offset:5120
	ds_read_b128 v[220:223], v171 offset:6144
	ds_read_b128 v[224:227], v171 offset:7168
	global_load_lds_dwordx4 v[158:159], off
	v_lshl_add_u64 v[158:159], s[20:21], 0, v[150:151]
	s_add_i32 m0, s36, 0xe000
	s_nop 0
	global_load_lds_dwordx4 v[158:159], off
	s_waitcnt vmcnt(8)
	s_waitcnt lgkmcnt(0)
	s_barrier
	s_setprio 1
	s_waitcnt lgkmcnt(0)
	v_mfma_i32_16x16x64_i8 v[134:137], v[90:93], v[196:199], v[134:137]
	v_mfma_i32_16x16x64_i8 v[130:133], v[172:175], v[196:199], v[130:133]
	v_mfma_i32_16x16x64_i8 v[118:121], v[90:93], v[204:207], v[118:121]
	v_mfma_i32_16x16x64_i8 v[114:117], v[172:175], v[204:207], v[114:117]
	v_mfma_i32_16x16x64_i8 v[102:105], v[90:93], v[212:215], v[102:105]
	v_mfma_i32_16x16x64_i8 v[94:97], v[172:175], v[212:215], v[94:97]
	v_mfma_i32_16x16x64_i8 v[78:81], v[90:93], v[220:223], v[78:81]
	v_mfma_i32_16x16x64_i8 v[74:77], v[172:175], v[220:223], v[74:77]
	v_mfma_i32_16x16x64_i8 v[134:137], v[98:101], v[200:203], v[134:137]
	v_mfma_i32_16x16x64_i8 v[130:133], v[176:179], v[200:203], v[130:133]
	v_mfma_i32_16x16x64_i8 v[118:121], v[98:101], v[208:211], v[118:121]
	v_mfma_i32_16x16x64_i8 v[114:117], v[176:179], v[208:211], v[114:117]
	v_mfma_i32_16x16x64_i8 v[102:105], v[98:101], v[216:219], v[102:105]
	v_mfma_i32_16x16x64_i8 v[94:97], v[176:179], v[216:219], v[94:97]
	v_mfma_i32_16x16x64_i8 v[78:81], v[98:101], v[224:227], v[78:81]
	v_mfma_i32_16x16x64_i8 v[74:77], v[176:179], v[224:227], v[74:77]
	s_setprio 0
	s_setprio 1
	v_mfma_i32_16x16x64_i8 v[126:129], v[180:183], v[196:199], v[126:129]
	v_mfma_i32_16x16x64_i8 v[122:125], v[188:191], v[196:199], v[122:125]
	v_mfma_i32_16x16x64_i8 v[110:113], v[180:183], v[204:207], v[110:113]
	v_mfma_i32_16x16x64_i8 v[106:109], v[188:191], v[204:207], v[106:109]
	v_mfma_i32_16x16x64_i8 v[86:89], v[180:183], v[212:215], v[86:89]
	v_mfma_i32_16x16x64_i8 v[82:85], v[188:191], v[212:215], v[82:85]
	v_mfma_i32_16x16x64_i8 v[70:73], v[180:183], v[220:223], v[70:73]
	v_mfma_i32_16x16x64_i8 v[66:69], v[188:191], v[220:223], v[66:69]
	v_mfma_i32_16x16x64_i8 v[126:129], v[184:187], v[200:203], v[126:129]
	v_mfma_i32_16x16x64_i8 v[122:125], v[192:195], v[200:203], v[122:125]
	v_mfma_i32_16x16x64_i8 v[110:113], v[184:187], v[208:211], v[110:113]
	v_mfma_i32_16x16x64_i8 v[106:109], v[192:195], v[208:211], v[106:109]
	v_mfma_i32_16x16x64_i8 v[86:89], v[184:187], v[216:219], v[86:89]
	v_mfma_i32_16x16x64_i8 v[82:85], v[192:195], v[216:219], v[82:85]
	v_mfma_i32_16x16x64_i8 v[70:73], v[184:187], v[224:227], v[70:73]
	v_mfma_i32_16x16x64_i8 v[66:69], v[192:195], v[224:227], v[66:69]
	s_setprio 0
	s_barrier
	s_add_i32 s54, s46, s33
	v_lshl_add_u64 v[158:159], s[24:25], 0, v[142:143]
	s_mov_b32 m0, s54
	ds_read_b128 v[196:199], v171 offset:16384
	ds_read_b128 v[200:203], v171 offset:17408
	ds_read_b128 v[204:207], v171 offset:18432
	ds_read_b128 v[208:211], v171 offset:19456
	ds_read_b128 v[212:215], v171 offset:20480
	ds_read_b128 v[216:219], v171 offset:21504
	ds_read_b128 v[220:223], v171 offset:22528
	ds_read_b128 v[224:227], v171 offset:23552
	global_load_lds_dwordx4 v[158:159], off
	s_add_i32 m0, s54, 0x2000
	s_add_u32 s54, s24, 0x4000
	v_lshl_add_u64 v[158:159], s[24:25], 0, v[138:139]
	s_addc_u32 s55, s25, 0
	s_add_i32 s56, s47, s33
	global_load_lds_dwordx4 v[158:159], off
	v_lshl_add_u64 v[158:159], s[54:55], 0, v[142:143]
	s_mov_b32 m0, s56
	s_nop 0
	global_load_lds_dwordx4 v[158:159], off
	v_lshl_add_u64 v[158:159], s[54:55], 0, v[138:139]
	s_add_i32 m0, s56, 0x2000
	s_nop 0
	global_load_lds_dwordx4 v[158:159], off
	s_waitcnt vmcnt(6)
	s_waitcnt lgkmcnt(0)
	s_barrier
; #define PG8_STAGE(bufoff, gbase, voff) do { _Pragma("unroll") for (int _i = 0; _i < 2; ++_i) \
;         __builtin_amdgcn_global_load_lds((const unsigned*)((const char*)(gbase) + (voff)[_i]), (LAS unsigned*)(lds + (bufoff) + ldsw + _i * 8192), 16, 0, 0); } while (0)
; #define PG8_LDA(dst, b, h) do { _Pragma("unroll") for (int m = 0; m < 4; ++m) _Pragma("unroll") for (int k = 0; k < 2; ++k) dst[m][k] = *(const LAS bf16x8*)(lds + PG8_SA(b, h) + aoff + m * 2048 + k * 1024); } while (0)
; #define PG8_LDB(dst, b, h) do { _Pragma("unroll") for (int n = 0; n < 2; ++n) _Pragma("unroll") for (int k = 0; k < 2; ++k) dst[n][k] = *(const LAS bf16x8*)(lds + PG8_SB(b, h) + boff + n * 2048 + k * 1024); } while (0)
; #define PG8_WAIT_V(n) asm volatile("s_waitcnt vmcnt(" #n ")" ::: "memory")
; #define PG8_WAIT_L(n) asm volatile("s_waitcnt lgkmcnt(" #n ")" ::: "memory")
; #define PG8_BAR __builtin_amdgcn_s_barrier()
; #define PG8_SCHED __builtin_amdgcn_sched_barrier(0)
; template <class Epi, class Sched, bool I8 = false>
; __device__ __forceinline__ void gemm_phase(LAS unsigned char* lds, const Gemm g, const Sched& S, const Epi& E) {
;     ...
;             PG8_WAIT_V(8); PG8_WAIT_L(0); PG8_BAR; PG8_MMA(1, 0, At, B0); PG8_MMA(1, 1, At, B1); PG8_BAR; PG8_SCHED;
;             PG8_LDB(B0, 1, 0); PG8_LDB(B1, 1, 1); PG8_SCHED; PG8_LDA(At, 1, 0); PG8_STAGE(PG8_SA(0, 1), a2 + hstepA, voffA);
;             PG8_WAIT_V(8); PG8_WAIT_L(0); PG8_BAR; PG8_MMA(0, 0, At, B0); PG8_MMA(0, 1, At, B1); PG8_BAR; PG8_SCHED;
	s_setprio 1
	s_waitcnt lgkmcnt(0)
	v_mfma_i32_16x16x64_i8 v[62:65], v[90:93], v[196:199], v[62:65]
	v_mfma_i32_16x16x64_i8 v[58:61], v[172:175], v[196:199], v[58:61]
	v_mfma_i32_16x16x64_i8 v[46:49], v[90:93], v[204:207], v[46:49]
	v_mfma_i32_16x16x64_i8 v[42:45], v[172:175], v[204:207], v[42:45]
	v_mfma_i32_16x16x64_i8 v[30:33], v[90:93], v[212:215], v[30:33]
	v_mfma_i32_16x16x64_i8 v[26:29], v[172:175], v[212:215], v[26:29]
	v_mfma_i32_16x16x64_i8 v[14:17], v[90:93], v[220:223], v[14:17]
	v_mfma_i32_16x16x64_i8 v[10:13], v[172:175], v[220:223], v[10:13]
	v_mfma_i32_16x16x64_i8 v[62:65], v[98:101], v[200:203], v[62:65]
	v_mfma_i32_16x16x64_i8 v[58:61], v[176:179], v[200:203], v[58:61]
	v_mfma_i32_16x16x64_i8 v[46:49], v[98:101], v[208:211], v[46:49]
	v_mfma_i32_16x16x64_i8 v[42:45], v[176:179], v[208:211], v[42:45]
	v_mfma_i32_16x16x64_i8 v[30:33], v[98:101], v[216:219], v[30:33]
	v_mfma_i32_16x16x64_i8 v[26:29], v[176:179], v[216:219], v[26:29]
	v_mfma_i32_16x16x64_i8 v[14:17], v[98:101], v[224:227], v[14:17]
	v_mfma_i32_16x16x64_i8 v[10:13], v[176:179], v[224:227], v[10:13]
	s_setprio 0
	s_setprio 1
	v_mfma_i32_16x16x64_i8 v[54:57], v[180:183], v[196:199], v[54:57]
	v_mfma_i32_16x16x64_i8 v[50:53], v[188:191], v[196:199], v[50:53]
	v_mfma_i32_16x16x64_i8 v[38:41], v[180:183], v[204:207], v[38:41]
	v_mfma_i32_16x16x64_i8 v[34:37], v[188:191], v[204:207], v[34:37]
	v_mfma_i32_16x16x64_i8 v[22:25], v[180:183], v[212:215], v[22:25]
	v_mfma_i32_16x16x64_i8 v[18:21], v[188:191], v[212:215], v[18:21]
	v_mfma_i32_16x16x64_i8 v[6:9], v[180:183], v[220:223], v[6:9]
	v_mfma_i32_16x16x64_i8 v[2:5], v[188:191], v[220:223], v[2:5]
	v_mfma_i32_16x16x64_i8 v[54:57], v[184:187], v[200:203], v[54:57]
	v_mfma_i32_16x16x64_i8 v[50:53], v[192:195], v[200:203], v[50:53]
	v_mfma_i32_16x16x64_i8 v[38:41], v[184:187], v[208:211], v[38:41]
	v_mfma_i32_16x16x64_i8 v[34:37], v[192:195], v[208:211], v[34:37]
	v_mfma_i32_16x16x64_i8 v[22:25], v[184:187], v[216:219], v[22:25]
	v_mfma_i32_16x16x64_i8 v[18:21], v[192:195], v[216:219], v[18:21]
	v_mfma_i32_16x16x64_i8 v[6:9], v[184:187], v[224:227], v[6:9]
	v_mfma_i32_16x16x64_i8 v[2:5], v[192:195], v[224:227], v[2:5]
	s_setprio 0
	s_barrier
	s_add_i32 s54, 0, 0x18000
	v_add_u32_e32 v146, s54, v165
	s_add_i32 s55, 0, 0x1c000
	ds_read_b128 v[90:93], v146
	ds_read_b128 v[98:101], v146 offset:1024
	ds_read_b128 v[172:175], v146 offset:2048
	ds_read_b128 v[176:179], v146 offset:3072
	v_add_u32_e32 v146, s55, v165
	ds_read_b128 v[180:183], v146
	ds_read_b128 v[184:187], v146 offset:1024
	ds_read_b128 v[188:191], v146 offset:2048
	ds_read_b128 v[192:195], v146 offset:3072
	v_lshl_add_u64 v[158:159], s[26:27], 0, v[144:145]
	s_mov_b32 m0, s36
	s_nop 0
	global_load_lds_dwordx4 v[158:159], off
	v_lshl_add_u64 v[158:159], s[26:27], 0, v[140:141]
	s_mov_b32 m0, s37
	s_nop 0
	global_load_lds_dwordx4 v[158:159], off
	s_add_u32 s26, s26, 0x4000
	s_addc_u32 s27, s27, 0
	s_mov_b32 m0, s38
	v_lshl_add_u64 v[158:159], s[26:27], 0, v[144:145]
	ds_read_b128 v[196:199], v171 offset:32768
	ds_read_b128 v[200:203], v171 offset:33792
	ds_read_b128 v[204:207], v171 offset:34816
	ds_read_b128 v[208:211], v171 offset:35840
	ds_read_b128 v[212:215], v171 offset:36864
	ds_read_b128 v[216:219], v171 offset:37888
	ds_read_b128 v[220:223], v171 offset:38912
	ds_read_b128 v[224:227], v171 offset:39936
	global_load_lds_dwordx4 v[158:159], off
	v_lshl_add_u64 v[158:159], s[26:27], 0, v[140:141]
	s_mov_b32 m0, s39
	s_nop 0
	global_load_lds_dwordx4 v[158:159], off
	s_waitcnt vmcnt(8)
	s_waitcnt lgkmcnt(0)
	s_barrier
; #define PG8_STAGE(bufoff, gbase, voff) do { _Pragma("unroll") for (int _i = 0; _i < 2; ++_i) \
;         __builtin_amdgcn_global_load_lds((const unsigned*)((const char*)(gbase) + (voff)[_i]), (LAS unsigned*)(lds + (bufoff) + ldsw + _i * 8192), 16, 0, 0); } while (0)
; #define PG8_LDA(dst, b, h) do { _Pragma("unroll") for (int m = 0; m < 4; ++m) _Pragma("unroll") for (int k = 0; k < 2; ++k) dst[m][k] = *(const LAS bf16x8*)(lds + PG8_SA(b, h) + aoff + m * 2048 + k * 1024); } while (0)
; #define PG8_WAIT_V(n) asm volatile("s_waitcnt vmcnt(" #n ")" ::: "memory")
; #define PG8_WAIT_L(n) asm volatile("s_waitcnt lgkmcnt(" #n ")" ::: "memory")
; #define PG8_BAR __builtin_amdgcn_s_barrier()
; #define PG8_SCHED __builtin_amdgcn_sched_barrier(0)
; template <class Epi, class Sched, bool I8 = false>
; __device__ __forceinline__ void gemm_phase(LAS unsigned char* lds, const Gemm g, const Sched& S, const Epi& E) {
;     ...
;             PG8_WAIT_V(8); PG8_WAIT_L(0); PG8_BAR; PG8_MMA(0, 0, At, B0); PG8_MMA(0, 1, At, B1); PG8_BAR; PG8_SCHED;
;             PG8_LDA(At, 1, 1); PG8_STAGE(PG8_SB(1, 0), b3, voffB); PG8_STAGE(PG8_SB(1, 1), b3 + hstepB, voffB); PG8_STAGE(PG8_SA(1, 0), a3, voffA);
;             PG8_WAIT_V(8); PG8_WAIT_L(0); PG8_BAR; PG8_MMA(1, 0, At, B0); PG8_MMA(1, 1, At, B1); PG8_BAR; PG8_SCHED;
;         }
	s_setprio 1
	s_waitcnt lgkmcnt(0)
	v_mfma_i32_16x16x64_i8 v[134:137], v[90:93], v[196:199], v[134:137]
	v_mfma_i32_16x16x64_i8 v[130:133], v[172:175], v[196:199], v[130:133]
	v_mfma_i32_16x16x64_i8 v[118:121], v[90:93], v[204:207], v[118:121]
	v_mfma_i32_16x16x64_i8 v[114:117], v[172:175], v[204:207], v[114:117]
	v_mfma_i32_16x16x64_i8 v[102:105], v[90:93], v[212:215], v[102:105]
	v_mfma_i32_16x16x64_i8 v[94:97], v[172:175], v[212:215], v[94:97]
	v_mfma_i32_16x16x64_i8 v[78:81], v[90:93], v[220:223], v[78:81]
	v_mfma_i32_16x16x64_i8 v[74:77], v[172:175], v[220:223], v[74:77]
	v_mfma_i32_16x16x64_i8 v[134:137], v[98:101], v[200:203], v[134:137]
	v_mfma_i32_16x16x64_i8 v[130:133], v[176:179], v[200:203], v[130:133]
	v_mfma_i32_16x16x64_i8 v[118:121], v[98:101], v[208:211], v[118:121]
	v_mfma_i32_16x16x64_i8 v[114:117], v[176:179], v[208:211], v[114:117]
	v_mfma_i32_16x16x64_i8 v[102:105], v[98:101], v[216:219], v[102:105]
	v_mfma_i32_16x16x64_i8 v[94:97], v[176:179], v[216:219], v[94:97]
	v_mfma_i32_16x16x64_i8 v[78:81], v[98:101], v[224:227], v[78:81]
	v_mfma_i32_16x16x64_i8 v[74:77], v[176:179], v[224:227], v[74:77]
	s_setprio 0
	s_setprio 1
	v_mfma_i32_16x16x64_i8 v[126:129], v[180:183], v[196:199], v[126:129]
	v_mfma_i32_16x16x64_i8 v[122:125], v[188:191], v[196:199], v[122:125]
	v_mfma_i32_16x16x64_i8 v[110:113], v[180:183], v[204:207], v[110:113]
	v_mfma_i32_16x16x64_i8 v[106:109], v[188:191], v[204:207], v[106:109]
	v_mfma_i32_16x16x64_i8 v[86:89], v[180:183], v[212:215], v[86:89]
	v_mfma_i32_16x16x64_i8 v[82:85], v[188:191], v[212:215], v[82:85]
	v_mfma_i32_16x16x64_i8 v[70:73], v[180:183], v[220:223], v[70:73]
	v_mfma_i32_16x16x64_i8 v[66:69], v[188:191], v[220:223], v[66:69]
	v_mfma_i32_16x16x64_i8 v[126:129], v[184:187], v[200:203], v[126:129]
	v_mfma_i32_16x16x64_i8 v[122:125], v[192:195], v[200:203], v[122:125]
	v_mfma_i32_16x16x64_i8 v[110:113], v[184:187], v[208:211], v[110:113]
	v_mfma_i32_16x16x64_i8 v[106:109], v[192:195], v[208:211], v[106:109]
	v_mfma_i32_16x16x64_i8 v[86:89], v[184:187], v[216:219], v[86:89]
	v_mfma_i32_16x16x64_i8 v[82:85], v[192:195], v[216:219], v[82:85]
	v_mfma_i32_16x16x64_i8 v[70:73], v[184:187], v[224:227], v[70:73]
	v_mfma_i32_16x16x64_i8 v[66:69], v[192:195], v[224:227], v[66:69]
	s_setprio 0
	s_barrier
	s_add_u32 s26, s24, 0x8000
	s_addc_u32 s27, s25, 0
	s_add_i32 s54, s54, s33
	v_lshl_add_u64 v[158:159], s[26:27], 0, v[142:143]
	s_mov_b32 m0, s54
	ds_read_b128 v[196:199], v171 offset:49152
	ds_read_b128 v[200:203], v171 offset:50176
	ds_read_b128 v[204:207], v171 offset:51200
	ds_read_b128 v[208:211], v171 offset:52224
	ds_read_b128 v[212:215], v171 offset:53248
	ds_read_b128 v[216:219], v171 offset:54272
	ds_read_b128 v[220:223], v171 offset:55296
	ds_read_b128 v[224:227], v171 offset:56320
	global_load_lds_dwordx4 v[158:159], off
	s_add_i32 m0, s54, 0x2000
	s_add_u32 s24, s24, 0xc000
	v_lshl_add_u64 v[158:159], s[26:27], 0, v[138:139]
	s_addc_u32 s25, s25, 0
	s_add_i32 s26, s55, s33
	global_load_lds_dwordx4 v[158:159], off
	v_lshl_add_u64 v[158:159], s[24:25], 0, v[142:143]
	s_mov_b32 m0, s26
	s_nop 0
	global_load_lds_dwordx4 v[158:159], off
	v_lshl_add_u64 v[158:159], s[24:25], 0, v[138:139]
	s_add_i32 m0, s26, 0x2000
	s_nop 0
	global_load_lds_dwordx4 v[158:159], off
	s_waitcnt vmcnt(6)
	s_waitcnt lgkmcnt(0)
	s_barrier
	s_setprio 1
	s_waitcnt lgkmcnt(0)
	v_mfma_i32_16x16x64_i8 v[62:65], v[90:93], v[196:199], v[62:65]
	v_mfma_i32_16x16x64_i8 v[58:61], v[172:175], v[196:199], v[58:61]
	v_mfma_i32_16x16x64_i8 v[46:49], v[90:93], v[204:207], v[46:49]
	v_mfma_i32_16x16x64_i8 v[42:45], v[172:175], v[204:207], v[42:45]
	v_mfma_i32_16x16x64_i8 v[30:33], v[90:93], v[212:215], v[30:33]
	v_mfma_i32_16x16x64_i8 v[26:29], v[172:175], v[212:215], v[26:29]
	v_mfma_i32_16x16x64_i8 v[14:17], v[90:93], v[220:223], v[14:17]
	v_mfma_i32_16x16x64_i8 v[10:13], v[172:175], v[220:223], v[10:13]
	v_mfma_i32_16x16x64_i8 v[62:65], v[98:101], v[200:203], v[62:65]
	v_mfma_i32_16x16x64_i8 v[58:61], v[176:179], v[200:203], v[58:61]
	v_mfma_i32_16x16x64_i8 v[46:49], v[98:101], v[208:211], v[46:49]
	v_mfma_i32_16x16x64_i8 v[42:45], v[176:179], v[208:211], v[42:45]
	v_mfma_i32_16x16x64_i8 v[30:33], v[98:101], v[216:219], v[30:33]
	v_mfma_i32_16x16x64_i8 v[26:29], v[176:179], v[216:219], v[26:29]
	v_mfma_i32_16x16x64_i8 v[14:17], v[98:101], v[224:227], v[14:17]
	v_mfma_i32_16x16x64_i8 v[10:13], v[176:179], v[224:227], v[10:13]
	s_setprio 0
	s_setprio 1
	v_mfma_i32_16x16x64_i8 v[54:57], v[180:183], v[196:199], v[54:57]
	v_mfma_i32_16x16x64_i8 v[50:53], v[188:191], v[196:199], v[50:53]
	v_mfma_i32_16x16x64_i8 v[38:41], v[180:183], v[204:207], v[38:41]
	v_mfma_i32_16x16x64_i8 v[34:37], v[188:191], v[204:207], v[34:37]
	v_mfma_i32_16x16x64_i8 v[22:25], v[180:183], v[212:215], v[22:25]
	v_mfma_i32_16x16x64_i8 v[18:21], v[188:191], v[212:215], v[18:21]
	v_mfma_i32_16x16x64_i8 v[6:9], v[180:183], v[220:223], v[6:9]
	v_mfma_i32_16x16x64_i8 v[2:5], v[188:191], v[220:223], v[2:5]
	v_mfma_i32_16x16x64_i8 v[54:57], v[184:187], v[200:203], v[54:57]
	v_mfma_i32_16x16x64_i8 v[50:53], v[192:195], v[200:203], v[50:53]
	v_mfma_i32_16x16x64_i8 v[38:41], v[184:187], v[208:211], v[38:41]
	v_mfma_i32_16x16x64_i8 v[34:37], v[192:195], v[208:211], v[34:37]
	v_mfma_i32_16x16x64_i8 v[22:25], v[184:187], v[216:219], v[22:25]
	v_mfma_i32_16x16x64_i8 v[18:21], v[192:195], v[216:219], v[18:21]
	v_mfma_i32_16x16x64_i8 v[6:9], v[184:187], v[224:227], v[6:9]
	v_mfma_i32_16x16x64_i8 v[2:5], v[192:195], v[224:227], v[2:5]
	s_setprio 0
	s_barrier
	s_add_i32 s53, s53, 2
	s_add_u32 s20, s20, 0x10000
	s_addc_u32 s21, s21, 0
	s_add_u32 s51, s51, 0x10000
	s_addc_u32 s52, s52, 0
	s_cmp_gt_u32 s53, 29
	s_cbranch_scc0 .LBB0_1169
	s_and_b64 vcc, exec, s[8:9]
	s_cbranch_vccz .LBB0_1172
	s_barrier
